# MoBA loop: waves 4-7 defer exp/PV half-step (stagger, no extra barrier), V tiles triple-buffered via 12KiB static LDS
# baseline (speedup 1.0000x reference)
.LBB0_906:
	s_lshl_b64 s[4:5], s[0:1], 18
	v_readlane_b32 s1, v240, 22
	s_add_u32 s2, s1, s4
	v_readlane_b32 s1, v240, 26
	s_addc_u32 s3, s1, s5
	v_readlane_b32 s1, v240, 34
	s_add_u32 s12, s1, s4
	v_readlane_b32 s1, v240, 35
	s_addc_u32 s13, s1, s5
	v_lshl_add_u64 v[0:1], s[2:3], 0, v[152:153]
	s_movk_i32 s1, 0x2000
	v_lshl_add_u64 v[2:3], s[12:13], 0, v[152:153]
	global_load_dwordx4 v[96:99], v[0:1], off
	global_load_dwordx4 v[100:103], v[2:3], off
	v_add_co_u32_e32 v0, vcc, s1, v0
	v_mov_b32_e32 v14, v151
	s_nop 0
	v_addc_co_u32_e32 v1, vcc, 0, v1, vcc
	v_add_co_u32_e32 v2, vcc, s1, v2
	v_mov_b32_e32 v15, v151
	s_nop 0
	v_addc_co_u32_e32 v3, vcc, 0, v3, vcc
	global_load_dwordx4 v[104:107], v[0:1], off
	global_load_dwordx4 v[108:111], v[2:3], off
	s_lshl_b32 s1, s93, 2
	v_mov_b32_e32 v0, v151
	v_mov_b32_e32 v1, v151
	v_mov_b32_e32 v2, v151
	v_mov_b32_e32 v3, v151
	v_mov_b32_e32 v4, v151
	v_mov_b32_e32 v5, v151
	v_mov_b32_e32 v6, v151
	v_mov_b32_e32 v7, v151
	v_mov_b32_e32 v8, v151
	v_mov_b32_e32 v9, v151
	v_mov_b32_e32 v10, v151
	v_mov_b32_e32 v11, v151
	v_mov_b32_e32 v12, v151
	v_mov_b32_e32 v13, v151
	v_mov_b64_e32 v[30:31], v[14:15]
	v_mov_b64_e32 v[46:47], v[14:15]
	s_or_b32 s2, s1, 3
	s_mov_b32 s3, 0
	v_lshl_add_u64 v[130:131], v[142:143], 0, s[4:5]
	v_mov_b32_e32 v147, 0
	v_mov_b32_e32 v148, 0
	v_mov_b64_e32 v[28:29], v[12:13]
	v_mov_b64_e32 v[26:27], v[10:11]
	v_mov_b64_e32 v[24:25], v[8:9]
	v_mov_b64_e32 v[22:23], v[6:7]
	v_mov_b64_e32 v[20:21], v[4:5]
	v_mov_b64_e32 v[18:19], v[2:3]
	v_mov_b64_e32 v[16:17], v[0:1]
	v_mov_b64_e32 v[44:45], v[12:13]
	v_mov_b64_e32 v[42:43], v[10:11]
	v_mov_b64_e32 v[40:41], v[8:9]
	v_mov_b64_e32 v[38:39], v[6:7]
	v_mov_b64_e32 v[36:37], v[4:5]
	v_mov_b64_e32 v[34:35], v[2:3]
	v_mov_b64_e32 v[32:33], v[0:1]
	s_mov_b32 s13, 0
	s_mov_b32 s98, 0
	s_mov_b32 s99, 0
	s_mov_b32 s100, 0
	v_readfirstlane_b32 s101, v188
	s_nop 3
	s_lshr_b32 s101, s101, 8
	s_cmp_lg_u32 s101, 0
	s_cbranch_scc1 .Lml_top
.LBB0_907:
	v_add_u32_e32 v149, v156, v157
	v_add_u32_e32 v212, v158, v157
	v_add_u32_e32 v250, s98, v212
	v_add_u32_e32 v248, s98, v160
	s_waitcnt vmcnt(2)
	ds_write_b128 v149, v[96:99]
	ds_write_b128 v250, v[100:103] offset:18432
	s_add_i32 s12, s13, 2
	s_add_u32 s98, s98, 0x3000
	s_cmp_eq_u32 s98, 0x6000
	s_cselect_b32 s98, 0x1f800, s98
	s_cmp_eq_u32 s98, 0x22800
	s_cselect_b32 s98, 0, s98
	s_waitcnt lgkmcnt(0)
	s_barrier
	s_cmp_gt_i32 s12, s2
	s_cselect_b64 s[48:49], -1, 0
	s_and_b64 vcc, exec, s[48:49]
	s_cbranch_vccnz .LBB0_909
	v_add_co_u32_e32 v48, vcc, 0xfdffe000, v130
	s_nop 1
	v_addc_co_u32_e32 v49, vcc, -1, v131, vcc
	v_add_co_u32_e32 v50, vcc, 0xffffe000, v130
	s_nop 1
	v_addc_co_u32_e32 v51, vcc, -1, v131, vcc
	global_load_dwordx4 v[96:99], v[48:49], off
	global_load_dwordx4 v[100:103], v[50:51], off

.LBB0_913:
	v_cmp_lt_i32_e32 vcc, -1, v213
	s_and_b64 s[4:5], s[14:15], vcc
	v_cndmask_b32_e64 v48, 0, 1, s[4:5]
	v_cmp_ne_u32_e32 vcc, 0, v48
	s_cbranch_vccz .LBB0_921
	v_add_u32_e32 v124, v159, v132
	v_cmp_lt_i32_e32 vcc, 62, v213
	s_xor_b64 s[52:53], s[4:5], -1
	ds_read_b128 v[112:115], v124
	ds_read_b128 v[116:119], v124 offset:32
	s_or_b64 s[16:17], vcc, s[52:53]
	v_cndmask_b32_e64 v48, 0, 1, s[16:17]
	s_and_b64 s[14:15], s[14:15], vcc
	v_cmp_ne_u32_e32 vcc, 0, v48
	s_cmp_lg_u64 vcc, exec
	s_cselect_b64 s[16:17], -1, 0
	s_or_b64 s[14:15], s[14:15], s[16:17]
	v_cndmask_b32_e64 v48, v210, 0, s[14:15]
	v_pk_add_f32 v[62:63], v[46:47], v[48:49] op_sel_hi:[1,0]
	v_pk_add_f32 v[60:61], v[44:45], v[48:49] op_sel_hi:[1,0]
	v_pk_add_f32 v[58:59], v[42:43], v[48:49] op_sel_hi:[1,0]
	v_pk_add_f32 v[56:57], v[40:41], v[48:49] op_sel_hi:[1,0]
	v_pk_add_f32 v[54:55], v[38:39], v[48:49] op_sel_hi:[1,0]
	v_pk_add_f32 v[52:53], v[36:37], v[48:49] op_sel_hi:[1,0]
	v_pk_add_f32 v[50:51], v[34:35], v[48:49] op_sel_hi:[1,0]
	v_pk_add_f32 v[48:49], v[32:33], v[48:49] op_sel_hi:[1,0]
	s_cmp_eq_u64 vcc, exec
	s_waitcnt lgkmcnt(1)
	v_mfma_f32_32x32x16_bf16 v[64:79], v[112:115], v[80:83], v[48:63]
	ds_read_b128 v[112:115], v124 offset:4608
	ds_read_b128 v[120:123], v124 offset:4640
	s_waitcnt lgkmcnt(1)
	v_mfma_f32_32x32x16_bf16 v[48:63], v[112:115], v[80:83], v[48:63]
	v_mfma_f32_32x32x16_bf16 v[64:79], v[116:119], v[84:87], v[64:79]
	ds_read_b128 v[112:115], v124 offset:64
	ds_read_b128 v[116:119], v124 offset:96
	s_waitcnt lgkmcnt(2)
	v_mfma_f32_32x32x16_bf16 v[48:63], v[120:123], v[84:87], v[48:63]
	s_waitcnt lgkmcnt(1)
	v_mfma_f32_32x32x16_bf16 v[64:79], v[112:115], v[88:91], v[64:79]
	ds_read_b128 v[112:115], v124 offset:4672
	ds_read_b128 v[214:217], v124 offset:4704
	s_waitcnt lgkmcnt(1)
	v_mfma_f32_32x32x16_bf16 v[48:63], v[112:115], v[88:91], v[48:63]
	v_mfma_f32_32x32x16_bf16 v[64:79], v[116:119], v[92:95], v[64:79]
	ds_read_b64_tr_b16 v[120:121], v248 offset:18432
	ds_read_b64_tr_b16 v[122:123], v248 offset:19968
	ds_read_b64_tr_b16 v[114:115], v248 offset:20032
	ds_read_b64_tr_b16 v[112:113], v248 offset:18496
	ds_read_b64_tr_b16 v[124:125], v248 offset:21504
	ds_read_b64_tr_b16 v[126:127], v248 offset:23040
	ds_read_b64_tr_b16 v[118:119], v248 offset:23104
	ds_read_b64_tr_b16 v[116:117], v248 offset:21568
	s_waitcnt lgkmcnt(8)
	v_mfma_f32_32x32x16_bf16 v[48:63], v[214:217], v[92:95], v[48:63]
	s_cbranch_scc1 .LBB0_918
	v_cmp_le_u32_e64 s[14:15], v161, v213
	v_cmp_le_u32_e64 s[16:17], v162, v213
	v_cmp_le_u32_e64 s[18:19], v164, v213
	v_cmp_le_u32_e64 s[20:21], v166, v213
	v_cmp_le_u32_e64 s[22:23], v168, v213
	v_cmp_le_u32_e64 s[24:25], v170, v213
	v_cmp_le_u32_e64 s[26:27], v172, v213
	v_cmp_le_u32_e64 s[28:29], v174, v213
	v_cmp_le_u32_e64 s[30:31], v176, v213
	v_cmp_le_u32_e64 s[34:35], v178, v213
	v_cmp_le_u32_e64 s[36:37], v180, v213
	v_cmp_le_u32_e64 s[38:39], v182, v213
	v_cmp_le_u32_e64 s[40:41], v184, v213
	v_cmp_le_u32_e64 s[42:43], v186, v213
	v_cmp_le_u32_e64 s[44:45], v189, v213
	s_and_b64 s[14:15], s[4:5], s[14:15]
	s_and_b64 s[16:17], s[4:5], s[16:17]
	s_and_b64 s[18:19], s[4:5], s[18:19]
	s_and_b64 s[20:21], s[4:5], s[20:21]
	s_and_b64 s[22:23], s[4:5], s[22:23]
	s_and_b64 s[24:25], s[4:5], s[24:25]
	s_and_b64 s[26:27], s[4:5], s[26:27]
	s_and_b64 s[28:29], s[4:5], s[28:29]
	s_and_b64 s[30:31], s[4:5], s[30:31]
	s_and_b64 s[34:35], s[4:5], s[34:35]
	s_and_b64 s[36:37], s[4:5], s[36:37]
	s_and_b64 s[38:39], s[4:5], s[38:39]
	s_and_b64 s[40:41], s[4:5], s[40:41]
	s_and_b64 s[42:43], s[4:5], s[42:43]
	s_and_b64 s[44:45], s[4:5], s[44:45]
	v_cmp_gt_u32_e64 s[46:47], v191, v213
	v_cmp_le_u32_e32 vcc, v138, v213
	v_cndmask_b32_e64 v48, v210, v48, s[14:15]
	v_cmp_lt_u32_e64 s[14:15], v138, v213
	v_cndmask_b32_e64 v49, v210, v49, s[16:17]
	v_cmp_le_u32_e64 s[16:17], v163, v213
	v_cndmask_b32_e64 v50, v210, v50, s[18:19]
	v_cmp_le_u32_e64 s[18:19], v165, v213
	v_cndmask_b32_e64 v51, v210, v51, s[20:21]
	v_cmp_le_u32_e64 s[20:21], v167, v213
	v_cndmask_b32_e64 v52, v210, v52, s[22:23]
	v_cmp_le_u32_e64 s[22:23], v169, v213
	v_cndmask_b32_e64 v53, v210, v53, s[24:25]
	v_cmp_le_u32_e64 s[24:25], v171, v213
	v_cndmask_b32_e64 v54, v210, v54, s[26:27]
	v_cmp_le_u32_e64 s[26:27], v173, v213
	v_cndmask_b32_e64 v55, v210, v55, s[28:29]
	v_cmp_le_u32_e64 s[28:29], v175, v213
	v_cndmask_b32_e64 v56, v210, v56, s[30:31]
	v_cmp_le_u32_e64 s[30:31], v177, v213
	v_cndmask_b32_e64 v57, v210, v57, s[34:35]
	v_cmp_le_u32_e64 s[34:35], v179, v213
	v_cndmask_b32_e64 v58, v210, v58, s[36:37]
	v_cmp_le_u32_e64 s[36:37], v181, v213
	v_cndmask_b32_e64 v59, v210, v59, s[38:39]
	v_cmp_le_u32_e64 s[38:39], v183, v213
	v_cndmask_b32_e64 v60, v210, v60, s[40:41]
	v_cmp_le_u32_e64 s[40:41], v185, v213
	v_cndmask_b32_e64 v61, v210, v61, s[42:43]
	v_cmp_le_u32_e64 s[42:43], v187, v213
	v_cndmask_b32_e64 v62, v210, v62, s[44:45]
	v_cmp_le_u32_e64 s[44:45], v190, v213
	s_or_b64 s[52:53], s[52:53], s[46:47]
	s_and_saveexec_b64 s[46:47], s[52:53]
	v_mov_b32_e32 v63, s33
	s_or_b64 exec, exec, s[46:47]
	s_and_b64 vcc, s[4:5], vcc
	v_cndmask_b32_e32 v64, v210, v64, vcc
	s_and_b64 vcc, s[4:5], s[14:15]
	v_cndmask_b32_e32 v65, v210, v65, vcc
	s_and_b64 vcc, s[4:5], s[16:17]
	v_cndmask_b32_e32 v66, v210, v66, vcc
	s_and_b64 vcc, s[4:5], s[18:19]
	v_cndmask_b32_e32 v67, v210, v67, vcc
	s_and_b64 vcc, s[4:5], s[20:21]
	v_cndmask_b32_e32 v68, v210, v68, vcc
	s_and_b64 vcc, s[4:5], s[22:23]
	v_cndmask_b32_e32 v69, v210, v69, vcc
	s_and_b64 vcc, s[4:5], s[24:25]
	v_cndmask_b32_e32 v70, v210, v70, vcc
	s_and_b64 vcc, s[4:5], s[26:27]
	v_cndmask_b32_e32 v71, v210, v71, vcc
	s_and_b64 vcc, s[4:5], s[28:29]
	v_cndmask_b32_e32 v72, v210, v72, vcc
	s_and_b64 vcc, s[4:5], s[30:31]
	v_cndmask_b32_e32 v73, v210, v73, vcc
	s_and_b64 vcc, s[4:5], s[34:35]
	v_cndmask_b32_e32 v74, v210, v74, vcc
	s_and_b64 vcc, s[4:5], s[36:37]
	v_cndmask_b32_e32 v75, v210, v75, vcc
	s_and_b64 vcc, s[4:5], s[38:39]
	v_cndmask_b32_e32 v76, v210, v76, vcc
	s_and_b64 vcc, s[4:5], s[40:41]
	v_cndmask_b32_e32 v77, v210, v77, vcc
	s_and_b64 vcc, s[4:5], s[42:43]
	v_cndmask_b32_e32 v78, v210, v78, vcc
	s_and_b64 vcc, s[4:5], s[44:45]
	v_cndmask_b32_e32 v79, v210, v79, vcc

.LBB0_920:
	v_exp_f32_e32 v215, v64
	v_exp_f32_e32 v214, v48
	v_exp_f32_e32 v217, v65
	v_exp_f32_e32 v216, v49
	v_exp_f32_e32 v219, v66
	v_exp_f32_e32 v218, v50
	v_exp_f32_e32 v221, v67
	v_exp_f32_e32 v225, v68
	v_exp_f32_e32 v69, v69
	v_exp_f32_e32 v227, v70
	v_exp_f32_e32 v71, v71
	v_pk_add_f32 v[48:49], v[214:215], 0 op_sel_hi:[1,0]
	v_exp_f32_e32 v220, v51
	v_pk_add_f32 v[48:49], v[216:217], v[48:49]
	v_cvt_pk_bf16_f32 v50, v225, v69
	v_pk_add_f32 v[222:223], v[218:219], v[48:49]
	v_cvt_pk_bf16_f32 v48, v215, v217
	v_cvt_pk_bf16_f32 v49, v219, v221
	v_cvt_pk_bf16_f32 v51, v227, v71
	v_exp_f32_e32 v229, v72
	v_exp_f32_e32 v73, v73
	s_waitcnt lgkmcnt(6)
	v_mfma_f32_32x32x16_bf16 v[0:15], v[120:123], v[48:51], v[0:15]
	v_exp_f32_e32 v231, v74
	v_exp_f32_e32 v75, v75
	v_exp_f32_e32 v233, v76
	v_exp_f32_e32 v77, v77
	v_exp_f32_e32 v121, v78
	v_exp_f32_e32 v79, v79
	v_cvt_pk_bf16_f32 v64, v229, v73
	s_waitcnt lgkmcnt(4)
	v_mfma_f32_32x32x16_bf16 v[16:31], v[112:115], v[48:51], v[16:31]
	v_cvt_pk_bf16_f32 v65, v231, v75
	v_cvt_pk_bf16_f32 v66, v233, v77
	v_cvt_pk_bf16_f32 v67, v121, v79
	v_exp_f32_e32 v224, v52
	v_exp_f32_e32 v68, v53
	v_exp_f32_e32 v226, v54
	v_exp_f32_e32 v70, v55
	s_waitcnt lgkmcnt(2)
	v_mfma_f32_32x32x16_bf16 v[0:15], v[124:127], v[64:67], v[0:15]
	ds_read_b64_tr_b16 v[48:49], v248 offset:24576
	ds_read_b64_tr_b16 v[50:51], v248 offset:26112
	v_exp_f32_e32 v228, v56
	v_exp_f32_e32 v72, v57
	v_exp_f32_e32 v230, v58
	v_exp_f32_e32 v74, v59
	ds_read_b64_tr_b16 v[52:53], v248 offset:27648
	ds_read_b64_tr_b16 v[54:55], v248 offset:29184
	ds_read_b64_tr_b16 v[58:59], v248 offset:26176
	ds_read_b64_tr_b16 v[56:57], v248 offset:24640
	v_exp_f32_e32 v232, v60
	s_waitcnt lgkmcnt(6)
	v_mfma_f32_32x32x16_bf16 v[16:31], v[116:119], v[64:67], v[16:31]
	v_cvt_pk_bf16_f32 v64, v214, v216
	v_cvt_pk_bf16_f32 v65, v218, v220
	v_cvt_pk_bf16_f32 v66, v224, v68
	v_cvt_pk_bf16_f32 v67, v226, v70
	v_exp_f32_e32 v76, v61
	v_exp_f32_e32 v120, v62
	v_exp_f32_e32 v78, v63
	s_waitcnt lgkmcnt(4)
	v_mfma_f32_32x32x16_bf16 v[0:15], v[48:51], v[64:67], v[0:15]
	v_add_f32_e64 v122, v220, v222
	v_add_f32_e64 v123, v221, v223
	v_cvt_pk_bf16_f32 v60, v228, v72
	v_cvt_pk_bf16_f32 v61, v230, v74
	v_cvt_pk_bf16_f32 v62, v232, v76
	v_cvt_pk_bf16_f32 v63, v120, v78
	ds_read_b64_tr_b16 v[50:51], v248 offset:29248
	ds_read_b64_tr_b16 v[48:49], v248 offset:27712
	s_waitcnt lgkmcnt(2)
	v_mfma_f32_32x32x16_bf16 v[16:31], v[56:59], v[64:67], v[16:31]
	v_mfma_f32_32x32x16_bf16 v[0:15], v[52:55], v[60:63], v[0:15]
	v_add_f32_e64 v52, v224, v122
	v_add_f32_e64 v53, v225, v123
	v_add_f32_e64 v52, v68, v52
	v_add_f32_e64 v53, v69, v53
	v_add_f32_e64 v52, v226, v52
	v_add_f32_e64 v53, v227, v53
	v_pk_add_f32 v[52:53], v[70:71], v[52:53]
	s_waitcnt lgkmcnt(0)
	v_mfma_f32_32x32x16_bf16 v[16:31], v[48:51], v[60:63], v[16:31]
	v_add_f32_e64 v52, v228, v52
	v_add_f32_e64 v53, v229, v53
	v_add_f32_e64 v52, v72, v52
	v_add_f32_e64 v53, v73, v53
	v_add_f32_e64 v52, v230, v52
	v_add_f32_e64 v53, v231, v53
	v_pk_add_f32 v[52:53], v[74:75], v[52:53]
	s_nop 0
	v_pk_add_f32 v[52:53], v[232:233], v[52:53]
	s_nop 0
	v_pk_add_f32 v[52:53], v[76:77], v[52:53]
	s_nop 0
	v_pk_add_f32 v[52:53], v[120:121], v[52:53]
	s_nop 0
	v_pk_add_f32 v[52:53], v[78:79], v[52:53]
	s_nop 0
	v_add_f32_e32 v52, v52, v53
	v_add_f32_e32 v147, v147, v52

.Lmoba_odd_ok:
	v_add_u32_e32 v250, s98, v212
	v_add_u32_e32 v249, s98, v160
	s_add_u32 s98, s98, 0x3000
	s_cmp_eq_u32 s98, 0x6000
	s_cselect_b32 s98, 0x1f800, s98
	s_cmp_eq_u32 s98, 0x22800
	s_cselect_b32 s98, 0, s98
	ds_write_b128 v149, v[104:107] offset:9216
	ds_write_b128 v250, v[108:111] offset:18432
	s_waitcnt lgkmcnt(0)
	s_barrier
	s_cmp_gt_i32 s13, s1
	s_cbranch_scc1 .LBB0_924
	v_add_co_u32_e32 v48, vcc, 0xfe000000, v130
	s_nop 1
	v_addc_co_u32_e32 v49, vcc, -1, v131, vcc
	global_load_dwordx4 v[104:107], v[48:49], off
	global_load_dwordx4 v[108:111], v[130:131], off

.LBB0_928:
	v_cmp_lt_i32_e32 vcc, -1, v149
	s_and_b64 s[4:5], s[14:15], vcc
	v_cndmask_b32_e64 v48, 0, 1, s[4:5]
	v_cmp_ne_u32_e32 vcc, 0, v48
	s_cbranch_vccz .LBB0_936
	v_add_u32_e32 v124, v159, v132
	v_cmp_lt_i32_e32 vcc, 62, v149
	s_xor_b64 s[50:51], s[4:5], -1
	ds_read_b128 v[112:115], v124 offset:9216
	ds_read_b128 v[116:119], v124 offset:9248
	s_or_b64 s[16:17], vcc, s[50:51]
	v_cndmask_b32_e64 v48, 0, 1, s[16:17]
	s_and_b64 s[14:15], s[14:15], vcc
	v_cmp_ne_u32_e32 vcc, 0, v48
	s_cmp_lg_u64 vcc, exec
	s_cselect_b64 s[16:17], -1, 0
	s_or_b64 s[14:15], s[14:15], s[16:17]
	v_cndmask_b32_e64 v48, v210, 0, s[14:15]
	v_pk_add_f32 v[62:63], v[46:47], v[48:49] op_sel_hi:[1,0]
	v_pk_add_f32 v[60:61], v[44:45], v[48:49] op_sel_hi:[1,0]
	v_pk_add_f32 v[58:59], v[42:43], v[48:49] op_sel_hi:[1,0]
	v_pk_add_f32 v[56:57], v[40:41], v[48:49] op_sel_hi:[1,0]
	v_pk_add_f32 v[54:55], v[38:39], v[48:49] op_sel_hi:[1,0]
	v_pk_add_f32 v[52:53], v[36:37], v[48:49] op_sel_hi:[1,0]
	v_pk_add_f32 v[50:51], v[34:35], v[48:49] op_sel_hi:[1,0]
	v_pk_add_f32 v[48:49], v[32:33], v[48:49] op_sel_hi:[1,0]
	s_cmp_eq_u64 vcc, exec
	s_waitcnt lgkmcnt(1)
	v_mfma_f32_32x32x16_bf16 v[64:79], v[112:115], v[80:83], v[48:63]
	ds_read_b128 v[112:115], v124 offset:13824
	ds_read_b128 v[120:123], v124 offset:13856
	s_waitcnt lgkmcnt(1)
	v_mfma_f32_32x32x16_bf16 v[48:63], v[112:115], v[80:83], v[48:63]
	v_mfma_f32_32x32x16_bf16 v[64:79], v[116:119], v[84:87], v[64:79]
	ds_read_b128 v[112:115], v124 offset:9280
	ds_read_b128 v[116:119], v124 offset:9312
	s_waitcnt lgkmcnt(2)
	v_mfma_f32_32x32x16_bf16 v[48:63], v[120:123], v[84:87], v[48:63]
	s_waitcnt lgkmcnt(1)
	v_mfma_f32_32x32x16_bf16 v[64:79], v[112:115], v[88:91], v[64:79]
	ds_read_b128 v[112:115], v124 offset:13888
	ds_read_b128 v[212:215], v124 offset:13920
	s_waitcnt lgkmcnt(1)
	v_mfma_f32_32x32x16_bf16 v[48:63], v[112:115], v[88:91], v[48:63]
	v_mfma_f32_32x32x16_bf16 v[64:79], v[116:119], v[92:95], v[64:79]
	ds_read_b64_tr_b16 v[120:121], v249 offset:18432
	ds_read_b64_tr_b16 v[122:123], v249 offset:19968
	ds_read_b64_tr_b16 v[114:115], v249 offset:20032
	ds_read_b64_tr_b16 v[112:113], v249 offset:18496
	ds_read_b64_tr_b16 v[124:125], v249 offset:21504
	ds_read_b64_tr_b16 v[126:127], v249 offset:23040
	ds_read_b64_tr_b16 v[118:119], v249 offset:23104
	ds_read_b64_tr_b16 v[116:117], v249 offset:21568
	s_waitcnt lgkmcnt(8)
	v_mfma_f32_32x32x16_bf16 v[48:63], v[212:215], v[92:95], v[48:63]
	s_cbranch_scc1 .LBB0_933
	v_cmp_le_u32_e64 s[14:15], v161, v149
	v_cmp_le_u32_e64 s[16:17], v162, v149
	v_cmp_le_u32_e64 s[18:19], v164, v149
	v_cmp_le_u32_e64 s[20:21], v166, v149
	v_cmp_le_u32_e64 s[22:23], v168, v149
	v_cmp_le_u32_e64 s[24:25], v170, v149
	v_cmp_le_u32_e64 s[26:27], v172, v149
	v_cmp_le_u32_e64 s[28:29], v174, v149
	v_cmp_le_u32_e64 s[30:31], v176, v149
	v_cmp_le_u32_e64 s[34:35], v178, v149
	v_cmp_le_u32_e64 s[36:37], v180, v149
	v_cmp_le_u32_e64 s[38:39], v182, v149
	v_cmp_le_u32_e64 s[40:41], v184, v149
	v_cmp_le_u32_e64 s[42:43], v186, v149
	v_cmp_le_u32_e64 s[44:45], v189, v149
	s_and_b64 s[14:15], s[4:5], s[14:15]
	s_and_b64 s[16:17], s[4:5], s[16:17]
	s_and_b64 s[18:19], s[4:5], s[18:19]
	s_and_b64 s[20:21], s[4:5], s[20:21]
	s_and_b64 s[22:23], s[4:5], s[22:23]
	s_and_b64 s[24:25], s[4:5], s[24:25]
	s_and_b64 s[26:27], s[4:5], s[26:27]
	s_and_b64 s[28:29], s[4:5], s[28:29]
	s_and_b64 s[30:31], s[4:5], s[30:31]
	s_and_b64 s[34:35], s[4:5], s[34:35]
	s_and_b64 s[36:37], s[4:5], s[36:37]
	s_and_b64 s[38:39], s[4:5], s[38:39]
	s_and_b64 s[40:41], s[4:5], s[40:41]
	s_and_b64 s[42:43], s[4:5], s[42:43]
	s_and_b64 s[44:45], s[4:5], s[44:45]
	v_cmp_gt_u32_e64 s[46:47], v191, v149
	v_cmp_le_u32_e32 vcc, v138, v149
	v_cndmask_b32_e64 v48, v210, v48, s[14:15]
	v_cmp_lt_u32_e64 s[14:15], v138, v149
	v_cndmask_b32_e64 v49, v210, v49, s[16:17]
	v_cmp_le_u32_e64 s[16:17], v163, v149
	v_cndmask_b32_e64 v50, v210, v50, s[18:19]
	v_cmp_le_u32_e64 s[18:19], v165, v149
	v_cndmask_b32_e64 v51, v210, v51, s[20:21]
	v_cmp_le_u32_e64 s[20:21], v167, v149
	v_cndmask_b32_e64 v52, v210, v52, s[22:23]
	v_cmp_le_u32_e64 s[22:23], v169, v149
	v_cndmask_b32_e64 v53, v210, v53, s[24:25]
	v_cmp_le_u32_e64 s[24:25], v171, v149
	v_cndmask_b32_e64 v54, v210, v54, s[26:27]
	v_cmp_le_u32_e64 s[26:27], v173, v149
	v_cndmask_b32_e64 v55, v210, v55, s[28:29]
	v_cmp_le_u32_e64 s[28:29], v175, v149
	v_cndmask_b32_e64 v56, v210, v56, s[30:31]
	v_cmp_le_u32_e64 s[30:31], v177, v149
	v_cndmask_b32_e64 v57, v210, v57, s[34:35]
	v_cmp_le_u32_e64 s[34:35], v179, v149
	v_cndmask_b32_e64 v58, v210, v58, s[36:37]
	v_cmp_le_u32_e64 s[36:37], v181, v149
	v_cndmask_b32_e64 v59, v210, v59, s[38:39]
	v_cmp_le_u32_e64 s[38:39], v183, v149
	v_cndmask_b32_e64 v60, v210, v60, s[40:41]
	v_cmp_le_u32_e64 s[40:41], v185, v149
	v_cndmask_b32_e64 v61, v210, v61, s[42:43]
	v_cmp_le_u32_e64 s[42:43], v187, v149
	v_cndmask_b32_e64 v62, v210, v62, s[44:45]
	v_cmp_le_u32_e64 s[44:45], v190, v149
	s_or_b64 s[50:51], s[50:51], s[46:47]
	s_and_saveexec_b64 s[46:47], s[50:51]
	v_mov_b32_e32 v63, s33
	s_or_b64 exec, exec, s[46:47]
	s_and_b64 vcc, s[4:5], vcc
	v_cndmask_b32_e32 v64, v210, v64, vcc
	s_and_b64 vcc, s[4:5], s[14:15]
	v_cndmask_b32_e32 v65, v210, v65, vcc
	s_and_b64 vcc, s[4:5], s[16:17]
	v_cndmask_b32_e32 v66, v210, v66, vcc
	s_and_b64 vcc, s[4:5], s[18:19]
	v_cndmask_b32_e32 v67, v210, v67, vcc
	s_and_b64 vcc, s[4:5], s[20:21]
	v_cndmask_b32_e32 v68, v210, v68, vcc
	s_and_b64 vcc, s[4:5], s[22:23]
	v_cndmask_b32_e32 v69, v210, v69, vcc
	s_and_b64 vcc, s[4:5], s[24:25]
	v_cndmask_b32_e32 v70, v210, v70, vcc
	s_and_b64 vcc, s[4:5], s[26:27]
	v_cndmask_b32_e32 v71, v210, v71, vcc
	s_and_b64 vcc, s[4:5], s[28:29]
	v_cndmask_b32_e32 v72, v210, v72, vcc
	s_and_b64 vcc, s[4:5], s[30:31]
	v_cndmask_b32_e32 v73, v210, v73, vcc
	s_and_b64 vcc, s[4:5], s[34:35]
	v_cndmask_b32_e32 v74, v210, v74, vcc
	s_and_b64 vcc, s[4:5], s[36:37]
	v_cndmask_b32_e32 v75, v210, v75, vcc
	s_and_b64 vcc, s[4:5], s[38:39]
	v_cndmask_b32_e32 v76, v210, v76, vcc
	s_and_b64 vcc, s[4:5], s[40:41]
	v_cndmask_b32_e32 v77, v210, v77, vcc
	s_and_b64 vcc, s[4:5], s[42:43]
	v_cndmask_b32_e32 v78, v210, v78, vcc
	s_and_b64 vcc, s[4:5], s[44:45]
	v_cndmask_b32_e32 v79, v210, v79, vcc

.LBB0_935:
	v_exp_f32_e32 v213, v64
	v_exp_f32_e32 v212, v48
	v_exp_f32_e32 v215, v65
	v_exp_f32_e32 v214, v49
	v_exp_f32_e32 v217, v66
	v_exp_f32_e32 v216, v50
	v_exp_f32_e32 v219, v67
	v_exp_f32_e32 v223, v68
	v_exp_f32_e32 v69, v69
	v_exp_f32_e32 v225, v70
	v_exp_f32_e32 v71, v71
	v_pk_add_f32 v[48:49], v[212:213], 0 op_sel_hi:[1,0]
	v_exp_f32_e32 v218, v51
	v_pk_add_f32 v[48:49], v[214:215], v[48:49]
	v_cvt_pk_bf16_f32 v50, v223, v69
	v_pk_add_f32 v[220:221], v[216:217], v[48:49]
	v_cvt_pk_bf16_f32 v48, v213, v215
	v_cvt_pk_bf16_f32 v49, v217, v219
	v_cvt_pk_bf16_f32 v51, v225, v71
	v_exp_f32_e32 v227, v72
	v_exp_f32_e32 v73, v73
	s_waitcnt lgkmcnt(6)
	v_mfma_f32_32x32x16_bf16 v[0:15], v[120:123], v[48:51], v[0:15]
	v_exp_f32_e32 v229, v74
	v_exp_f32_e32 v75, v75
	v_exp_f32_e32 v231, v76
	v_exp_f32_e32 v77, v77
	v_exp_f32_e32 v121, v78
	v_exp_f32_e32 v79, v79
	v_cvt_pk_bf16_f32 v64, v227, v73
	s_waitcnt lgkmcnt(4)
	v_mfma_f32_32x32x16_bf16 v[16:31], v[112:115], v[48:51], v[16:31]
	v_cvt_pk_bf16_f32 v65, v229, v75
	v_cvt_pk_bf16_f32 v66, v231, v77
	v_cvt_pk_bf16_f32 v67, v121, v79
	v_exp_f32_e32 v222, v52
	v_exp_f32_e32 v68, v53
	v_exp_f32_e32 v224, v54
	v_exp_f32_e32 v70, v55
	s_waitcnt lgkmcnt(2)
	v_mfma_f32_32x32x16_bf16 v[0:15], v[124:127], v[64:67], v[0:15]
	ds_read_b64_tr_b16 v[48:49], v249 offset:24576
	ds_read_b64_tr_b16 v[50:51], v249 offset:26112
	v_exp_f32_e32 v226, v56
	v_exp_f32_e32 v72, v57
	v_exp_f32_e32 v228, v58
	v_exp_f32_e32 v74, v59
	ds_read_b64_tr_b16 v[52:53], v249 offset:27648
	ds_read_b64_tr_b16 v[54:55], v249 offset:29184
	ds_read_b64_tr_b16 v[58:59], v249 offset:26176
	ds_read_b64_tr_b16 v[56:57], v249 offset:24640
	v_exp_f32_e32 v230, v60
	s_waitcnt lgkmcnt(6)
	v_mfma_f32_32x32x16_bf16 v[16:31], v[116:119], v[64:67], v[16:31]
	v_cvt_pk_bf16_f32 v64, v212, v214
	v_cvt_pk_bf16_f32 v65, v216, v218
	v_cvt_pk_bf16_f32 v66, v222, v68
	v_cvt_pk_bf16_f32 v67, v224, v70
	v_exp_f32_e32 v76, v61
	v_exp_f32_e32 v120, v62
	v_exp_f32_e32 v78, v63
	s_waitcnt lgkmcnt(4)
	v_mfma_f32_32x32x16_bf16 v[0:15], v[48:51], v[64:67], v[0:15]
	v_add_f32_e64 v122, v218, v220
	v_add_f32_e64 v123, v219, v221
	v_cvt_pk_bf16_f32 v60, v226, v72
	v_cvt_pk_bf16_f32 v61, v228, v74
	v_cvt_pk_bf16_f32 v62, v230, v76
	v_cvt_pk_bf16_f32 v63, v120, v78
	ds_read_b64_tr_b16 v[50:51], v249 offset:29248
	ds_read_b64_tr_b16 v[48:49], v249 offset:27712
	s_waitcnt lgkmcnt(2)
	v_mfma_f32_32x32x16_bf16 v[16:31], v[56:59], v[64:67], v[16:31]
	v_mfma_f32_32x32x16_bf16 v[0:15], v[52:55], v[60:63], v[0:15]
	v_add_f32_e64 v52, v222, v122
	v_add_f32_e64 v53, v223, v123
	v_add_f32_e64 v52, v68, v52
	v_add_f32_e64 v53, v69, v53
	v_add_f32_e64 v52, v224, v52
	v_add_f32_e64 v53, v225, v53
	v_pk_add_f32 v[52:53], v[70:71], v[52:53]
	s_waitcnt lgkmcnt(0)
	v_mfma_f32_32x32x16_bf16 v[16:31], v[48:51], v[60:63], v[16:31]
	v_add_f32_e64 v52, v226, v52
	v_add_f32_e64 v53, v227, v53
	v_add_f32_e64 v52, v72, v52
	v_add_f32_e64 v53, v73, v53
	v_add_f32_e64 v52, v228, v52
	v_add_f32_e64 v53, v229, v53
	v_pk_add_f32 v[52:53], v[74:75], v[52:53]
	s_nop 0
	v_pk_add_f32 v[52:53], v[230:231], v[52:53]
	s_nop 0
	v_pk_add_f32 v[52:53], v[76:77], v[52:53]
	s_nop 0
	v_pk_add_f32 v[52:53], v[120:121], v[52:53]
	s_nop 0
	v_pk_add_f32 v[52:53], v[78:79], v[52:53]
	s_nop 0
	v_add_f32_e32 v52, v52, v53
	v_add_f32_e32 v147, v147, v52

.Lme_fast:
	v_lshrrev_b32_e32 v48, s54, v146
	v_and_b32_e32 v48, 1, v48
	v_cmp_eq_u32_e32 vcc, 1, v48
	s_cbranch_vccz .LBB0_921
	v_add_u32_e32 v124, v159, v132
	s_nop 0
	v_cndmask_b32_e64 v48, v210, 0, vcc
	v_pk_add_f32 v[62:63], v[46:47], v[48:49] op_sel_hi:[1,0]
	v_pk_add_f32 v[60:61], v[44:45], v[48:49] op_sel_hi:[1,0]
	v_pk_add_f32 v[58:59], v[42:43], v[48:49] op_sel_hi:[1,0]
	v_pk_add_f32 v[56:57], v[40:41], v[48:49] op_sel_hi:[1,0]
	v_pk_add_f32 v[54:55], v[38:39], v[48:49] op_sel_hi:[1,0]
	v_pk_add_f32 v[52:53], v[36:37], v[48:49] op_sel_hi:[1,0]
	v_pk_add_f32 v[50:51], v[34:35], v[48:49] op_sel_hi:[1,0]
	v_pk_add_f32 v[48:49], v[32:33], v[48:49] op_sel_hi:[1,0]
	ds_read_b128 v[112:115], v124
	ds_read_b128 v[116:119], v124 offset:32
	s_waitcnt lgkmcnt(1)
	v_mfma_f32_32x32x16_bf16 v[64:79], v[112:115], v[80:83], v[48:63]
	ds_read_b128 v[112:115], v124 offset:4608
	ds_read_b128 v[120:123], v124 offset:4640
	s_waitcnt lgkmcnt(1)
	v_mfma_f32_32x32x16_bf16 v[48:63], v[112:115], v[80:83], v[48:63]
	v_mfma_f32_32x32x16_bf16 v[64:79], v[116:119], v[84:87], v[64:79]
	ds_read_b128 v[112:115], v124 offset:64
	ds_read_b128 v[116:119], v124 offset:96
	s_waitcnt lgkmcnt(2)
	v_mfma_f32_32x32x16_bf16 v[48:63], v[120:123], v[84:87], v[48:63]
	s_waitcnt lgkmcnt(1)
	v_mfma_f32_32x32x16_bf16 v[64:79], v[112:115], v[88:91], v[64:79]
	ds_read_b128 v[112:115], v124 offset:4672
	ds_read_b128 v[214:217], v124 offset:4704
	s_waitcnt lgkmcnt(1)
	v_mfma_f32_32x32x16_bf16 v[48:63], v[112:115], v[88:91], v[48:63]
	v_mfma_f32_32x32x16_bf16 v[64:79], v[116:119], v[92:95], v[64:79]
	ds_read_b64_tr_b16 v[120:121], v248 offset:18432
	ds_read_b64_tr_b16 v[122:123], v248 offset:19968
	ds_read_b64_tr_b16 v[114:115], v248 offset:20032
	ds_read_b64_tr_b16 v[112:113], v248 offset:18496
	ds_read_b64_tr_b16 v[124:125], v248 offset:21504
	ds_read_b64_tr_b16 v[126:127], v248 offset:23040
	ds_read_b64_tr_b16 v[118:119], v248 offset:23104
	ds_read_b64_tr_b16 v[116:117], v248 offset:21568
	s_waitcnt lgkmcnt(8)
	v_mfma_f32_32x32x16_bf16 v[48:63], v[214:217], v[92:95], v[48:63]
	s_branch .LBB0_918
.Lmo_fast:
	v_lshrrev_b32_e32 v48, s54, v146
	v_and_b32_e32 v48, 1, v48
	v_cmp_eq_u32_e32 vcc, 1, v48
	s_cbranch_vccz .LBB0_936
	v_add_u32_e32 v124, v159, v132
	s_nop 0
	v_cndmask_b32_e64 v48, v210, 0, vcc
	v_pk_add_f32 v[62:63], v[46:47], v[48:49] op_sel_hi:[1,0]
	v_pk_add_f32 v[60:61], v[44:45], v[48:49] op_sel_hi:[1,0]
	v_pk_add_f32 v[58:59], v[42:43], v[48:49] op_sel_hi:[1,0]
	v_pk_add_f32 v[56:57], v[40:41], v[48:49] op_sel_hi:[1,0]
	v_pk_add_f32 v[54:55], v[38:39], v[48:49] op_sel_hi:[1,0]
	v_pk_add_f32 v[52:53], v[36:37], v[48:49] op_sel_hi:[1,0]
	v_pk_add_f32 v[50:51], v[34:35], v[48:49] op_sel_hi:[1,0]
	v_pk_add_f32 v[48:49], v[32:33], v[48:49] op_sel_hi:[1,0]
	ds_read_b128 v[112:115], v124 offset:9216
	ds_read_b128 v[116:119], v124 offset:9248
	s_waitcnt lgkmcnt(1)
	v_mfma_f32_32x32x16_bf16 v[64:79], v[112:115], v[80:83], v[48:63]
	ds_read_b128 v[112:115], v124 offset:13824
	ds_read_b128 v[120:123], v124 offset:13856
	s_waitcnt lgkmcnt(1)
	v_mfma_f32_32x32x16_bf16 v[48:63], v[112:115], v[80:83], v[48:63]
	v_mfma_f32_32x32x16_bf16 v[64:79], v[116:119], v[84:87], v[64:79]
	ds_read_b128 v[112:115], v124 offset:9280
	ds_read_b128 v[116:119], v124 offset:9312
	s_waitcnt lgkmcnt(2)
	v_mfma_f32_32x32x16_bf16 v[48:63], v[120:123], v[84:87], v[48:63]
	s_waitcnt lgkmcnt(1)
	v_mfma_f32_32x32x16_bf16 v[64:79], v[112:115], v[88:91], v[64:79]
	ds_read_b128 v[112:115], v124 offset:13888
	ds_read_b128 v[212:215], v124 offset:13920
	s_waitcnt lgkmcnt(1)
	v_mfma_f32_32x32x16_bf16 v[48:63], v[112:115], v[88:91], v[48:63]
	v_mfma_f32_32x32x16_bf16 v[64:79], v[116:119], v[92:95], v[64:79]
	ds_read_b64_tr_b16 v[120:121], v249 offset:18432
	ds_read_b64_tr_b16 v[122:123], v249 offset:19968
	ds_read_b64_tr_b16 v[114:115], v249 offset:20032
	ds_read_b64_tr_b16 v[112:113], v249 offset:18496
	ds_read_b64_tr_b16 v[124:125], v249 offset:21504
	ds_read_b64_tr_b16 v[126:127], v249 offset:23040
	ds_read_b64_tr_b16 v[118:119], v249 offset:23104
	ds_read_b64_tr_b16 v[116:117], v249 offset:21568
	s_waitcnt lgkmcnt(8)
	v_mfma_f32_32x32x16_bf16 v[48:63], v[212:215], v[92:95], v[48:63]
	s_branch .LBB0_933
.Lml_top:
	v_add_u32_e32 v149, v156, v157
	v_add_u32_e32 v212, v158, v157
	v_add_u32_e32 v250, s98, v212
	v_add_u32_e32 v248, s98, v160
	s_waitcnt vmcnt(2)
	ds_write_b128 v149, v[96:99]
	ds_write_b128 v250, v[100:103] offset:18432
	s_add_i32 s12, s13, 2
	s_add_u32 s98, s98, 0x3000
	s_cmp_eq_u32 s98, 0x6000
	s_cselect_b32 s98, 0x1f800, s98
	s_cmp_eq_u32 s98, 0x22800
	s_cselect_b32 s98, 0, s98
	s_waitcnt lgkmcnt(0)
	s_barrier
	s_cmp_gt_i32 s12, s2
	s_cselect_b64 s[48:49], -1, 0
	s_and_b64 vcc, exec, s[48:49]
	s_cbranch_vccnz .Lml_909
	v_add_co_u32_e32 v242, vcc, 0xfdffe000, v130
	s_nop 1
	v_addc_co_u32_e32 v243, vcc, -1, v131, vcc
	v_add_co_u32_e32 v244, vcc, 0xffffe000, v130
	s_nop 1
	v_addc_co_u32_e32 v245, vcc, -1, v131, vcc
	global_load_dwordx4 v[96:99], v[242:243], off
	global_load_dwordx4 v[100:103], v[244:245], off
.Lml_909:
	s_cmp_eq_u32 s99, 0
	s_cbranch_scc1 .Lml_noc2_e
	v_exp_f32_e32 v247, v64
	v_exp_f32_e32 v246, v48
	v_exp_f32_e32 v215, v65
	v_exp_f32_e32 v214, v49
	v_exp_f32_e32 v217, v66
	v_exp_f32_e32 v216, v50
	v_exp_f32_e32 v219, v67
	v_exp_f32_e32 v223, v68
	v_exp_f32_e32 v69, v69
	v_exp_f32_e32 v225, v70
	v_exp_f32_e32 v71, v71
	v_pk_add_f32 v[48:49], v[246:247], 0 op_sel_hi:[1,0]
	v_exp_f32_e32 v218, v51
	v_pk_add_f32 v[48:49], v[214:215], v[48:49]
	v_cvt_pk_bf16_f32 v50, v223, v69
	v_pk_add_f32 v[220:221], v[216:217], v[48:49]
	v_cvt_pk_bf16_f32 v48, v247, v215
	v_cvt_pk_bf16_f32 v49, v217, v219
	v_cvt_pk_bf16_f32 v51, v225, v71
	v_exp_f32_e32 v227, v72
	v_exp_f32_e32 v73, v73
	s_waitcnt lgkmcnt(6)
	v_mfma_f32_32x32x16_bf16 v[0:15], v[120:123], v[48:51], v[0:15]
	v_exp_f32_e32 v229, v74
	v_exp_f32_e32 v75, v75
	v_exp_f32_e32 v231, v76
	v_exp_f32_e32 v77, v77
	v_exp_f32_e32 v121, v78
	v_exp_f32_e32 v79, v79
	v_cvt_pk_bf16_f32 v64, v227, v73
	s_waitcnt lgkmcnt(4)
	v_mfma_f32_32x32x16_bf16 v[16:31], v[112:115], v[48:51], v[16:31]
	v_cvt_pk_bf16_f32 v65, v229, v75
	v_cvt_pk_bf16_f32 v66, v231, v77
	v_cvt_pk_bf16_f32 v67, v121, v79
	v_exp_f32_e32 v222, v52
	v_exp_f32_e32 v68, v53
	v_exp_f32_e32 v224, v54
	v_exp_f32_e32 v70, v55
	s_waitcnt lgkmcnt(2)
	v_mfma_f32_32x32x16_bf16 v[0:15], v[124:127], v[64:67], v[0:15]
	ds_read_b64_tr_b16 v[48:49], v249 offset:24576
	ds_read_b64_tr_b16 v[50:51], v249 offset:26112
	v_exp_f32_e32 v226, v56
	v_exp_f32_e32 v72, v57
	v_exp_f32_e32 v228, v58
	v_exp_f32_e32 v74, v59
	ds_read_b64_tr_b16 v[52:53], v249 offset:27648
	ds_read_b64_tr_b16 v[54:55], v249 offset:29184
	ds_read_b64_tr_b16 v[58:59], v249 offset:26176
	ds_read_b64_tr_b16 v[56:57], v249 offset:24640
	v_exp_f32_e32 v230, v60
	s_waitcnt lgkmcnt(6)
	v_mfma_f32_32x32x16_bf16 v[16:31], v[116:119], v[64:67], v[16:31]
	v_cvt_pk_bf16_f32 v64, v246, v214
	v_cvt_pk_bf16_f32 v65, v216, v218
	v_cvt_pk_bf16_f32 v66, v222, v68
	v_cvt_pk_bf16_f32 v67, v224, v70
	v_exp_f32_e32 v76, v61
	v_exp_f32_e32 v120, v62
	v_exp_f32_e32 v78, v63
	s_waitcnt lgkmcnt(4)
	v_mfma_f32_32x32x16_bf16 v[0:15], v[48:51], v[64:67], v[0:15]
	v_add_f32_e64 v122, v218, v220
	v_add_f32_e64 v123, v219, v221
	v_cvt_pk_bf16_f32 v60, v226, v72
	v_cvt_pk_bf16_f32 v61, v228, v74
	v_cvt_pk_bf16_f32 v62, v230, v76
	v_cvt_pk_bf16_f32 v63, v120, v78
	ds_read_b64_tr_b16 v[50:51], v249 offset:29248
	ds_read_b64_tr_b16 v[48:49], v249 offset:27712
	s_waitcnt lgkmcnt(2)
	v_mfma_f32_32x32x16_bf16 v[16:31], v[56:59], v[64:67], v[16:31]
	v_mfma_f32_32x32x16_bf16 v[0:15], v[52:55], v[60:63], v[0:15]
	v_add_f32_e64 v52, v222, v122
	v_add_f32_e64 v53, v223, v123
	v_add_f32_e64 v52, v68, v52
	v_add_f32_e64 v53, v69, v53
	v_add_f32_e64 v52, v224, v52
	v_add_f32_e64 v53, v225, v53
	v_pk_add_f32 v[52:53], v[70:71], v[52:53]
	s_waitcnt lgkmcnt(0)
	v_mfma_f32_32x32x16_bf16 v[16:31], v[48:51], v[60:63], v[16:31]
	v_add_f32_e64 v52, v226, v52
	v_add_f32_e64 v53, v227, v53
	v_add_f32_e64 v52, v72, v52
	v_add_f32_e64 v53, v73, v53
	v_add_f32_e64 v52, v228, v52
	v_add_f32_e64 v53, v229, v53
	v_pk_add_f32 v[52:53], v[74:75], v[52:53]
	s_nop 0
	v_pk_add_f32 v[52:53], v[230:231], v[52:53]
	s_nop 0
	v_pk_add_f32 v[52:53], v[76:77], v[52:53]
	s_nop 0
	v_pk_add_f32 v[52:53], v[120:121], v[52:53]
	s_nop 0
	v_pk_add_f32 v[52:53], v[78:79], v[52:53]
	s_nop 0
	v_add_f32_e32 v52, v52, v53
	v_add_f32_e32 v147, v147, v52

.Lml_c1e_done:
	s_mov_b32 s99, 1
	s_mov_b32 s100, 0
	s_branch .Lml_921x
.Lml_skip_e:
	s_mov_b32 s99, 0

.Lml_Lmobaoddok:
	v_add_u32_e32 v250, s98, v212
	v_add_u32_e32 v249, s98, v160
	s_add_u32 s98, s98, 0x3000
	s_cmp_eq_u32 s98, 0x6000
	s_cselect_b32 s98, 0x1f800, s98
	s_cmp_eq_u32 s98, 0x22800
	s_cselect_b32 s98, 0, s98
	ds_write_b128 v149, v[104:107] offset:9216
	ds_write_b128 v250, v[108:111] offset:18432
	s_waitcnt lgkmcnt(0)
	s_barrier
	s_cmp_gt_i32 s13, s1
	s_cbranch_scc1 .Lml_924
	v_add_co_u32_e32 v242, vcc, 0xfe000000, v130
	s_nop 1
	v_addc_co_u32_e32 v243, vcc, -1, v131, vcc
	global_load_dwordx4 v[104:107], v[242:243], off
	global_load_dwordx4 v[108:111], v[130:131], off
.Lml_924:
	s_cmp_eq_u32 s99, 0
	s_cbranch_scc1 .Lml_noc2_o
	v_exp_f32_e32 v215, v64
	v_exp_f32_e32 v214, v48
	v_exp_f32_e32 v217, v65
	v_exp_f32_e32 v216, v49
	v_exp_f32_e32 v219, v66
	v_exp_f32_e32 v218, v50
	v_exp_f32_e32 v221, v67
	v_exp_f32_e32 v225, v68
	v_exp_f32_e32 v69, v69
	v_exp_f32_e32 v227, v70
	v_exp_f32_e32 v71, v71
	v_pk_add_f32 v[48:49], v[214:215], 0 op_sel_hi:[1,0]
	v_exp_f32_e32 v220, v51
	v_pk_add_f32 v[48:49], v[216:217], v[48:49]
	v_cvt_pk_bf16_f32 v50, v225, v69
	v_pk_add_f32 v[222:223], v[218:219], v[48:49]
	v_cvt_pk_bf16_f32 v48, v215, v217
	v_cvt_pk_bf16_f32 v49, v219, v221
	v_cvt_pk_bf16_f32 v51, v227, v71
	v_exp_f32_e32 v229, v72
	v_exp_f32_e32 v73, v73
	s_waitcnt lgkmcnt(6)
	v_mfma_f32_32x32x16_bf16 v[0:15], v[120:123], v[48:51], v[0:15]
	v_exp_f32_e32 v231, v74
	v_exp_f32_e32 v75, v75
	v_exp_f32_e32 v233, v76
	v_exp_f32_e32 v77, v77
	v_exp_f32_e32 v121, v78
	v_exp_f32_e32 v79, v79
	v_cvt_pk_bf16_f32 v64, v229, v73
	s_waitcnt lgkmcnt(4)
	v_mfma_f32_32x32x16_bf16 v[16:31], v[112:115], v[48:51], v[16:31]
	v_cvt_pk_bf16_f32 v65, v231, v75
	v_cvt_pk_bf16_f32 v66, v233, v77
	v_cvt_pk_bf16_f32 v67, v121, v79
	v_exp_f32_e32 v224, v52
	v_exp_f32_e32 v68, v53
	v_exp_f32_e32 v226, v54
	v_exp_f32_e32 v70, v55
	s_waitcnt lgkmcnt(2)
	v_mfma_f32_32x32x16_bf16 v[0:15], v[124:127], v[64:67], v[0:15]
	ds_read_b64_tr_b16 v[48:49], v248 offset:24576
	ds_read_b64_tr_b16 v[50:51], v248 offset:26112
	v_exp_f32_e32 v228, v56
	v_exp_f32_e32 v72, v57
	v_exp_f32_e32 v230, v58
	v_exp_f32_e32 v74, v59
	ds_read_b64_tr_b16 v[52:53], v248 offset:27648
	ds_read_b64_tr_b16 v[54:55], v248 offset:29184
	ds_read_b64_tr_b16 v[58:59], v248 offset:26176
	ds_read_b64_tr_b16 v[56:57], v248 offset:24640
	v_exp_f32_e32 v232, v60
	s_waitcnt lgkmcnt(6)
	v_mfma_f32_32x32x16_bf16 v[16:31], v[116:119], v[64:67], v[16:31]
	v_cvt_pk_bf16_f32 v64, v214, v216
	v_cvt_pk_bf16_f32 v65, v218, v220
	v_cvt_pk_bf16_f32 v66, v224, v68
	v_cvt_pk_bf16_f32 v67, v226, v70
	v_exp_f32_e32 v76, v61
	v_exp_f32_e32 v120, v62
	v_exp_f32_e32 v78, v63
	s_waitcnt lgkmcnt(4)
	v_mfma_f32_32x32x16_bf16 v[0:15], v[48:51], v[64:67], v[0:15]
	v_add_f32_e64 v122, v220, v222
	v_add_f32_e64 v123, v221, v223
	v_cvt_pk_bf16_f32 v60, v228, v72
	v_cvt_pk_bf16_f32 v61, v230, v74
	v_cvt_pk_bf16_f32 v62, v232, v76
	v_cvt_pk_bf16_f32 v63, v120, v78
	ds_read_b64_tr_b16 v[50:51], v248 offset:29248
	ds_read_b64_tr_b16 v[48:49], v248 offset:27712
	s_waitcnt lgkmcnt(2)
	v_mfma_f32_32x32x16_bf16 v[16:31], v[56:59], v[64:67], v[16:31]
	v_mfma_f32_32x32x16_bf16 v[0:15], v[52:55], v[60:63], v[0:15]
	v_add_f32_e64 v52, v224, v122
	v_add_f32_e64 v53, v225, v123
	v_add_f32_e64 v52, v68, v52
	v_add_f32_e64 v53, v69, v53
	v_add_f32_e64 v52, v226, v52
	v_add_f32_e64 v53, v227, v53
	v_pk_add_f32 v[52:53], v[70:71], v[52:53]
	s_waitcnt lgkmcnt(0)
	v_mfma_f32_32x32x16_bf16 v[16:31], v[48:51], v[60:63], v[16:31]
	v_add_f32_e64 v52, v228, v52
	v_add_f32_e64 v53, v229, v53
	v_add_f32_e64 v52, v72, v52
	v_add_f32_e64 v53, v73, v53
	v_add_f32_e64 v52, v230, v52
	v_add_f32_e64 v53, v231, v53
	v_pk_add_f32 v[52:53], v[74:75], v[52:53]
	s_nop 0
	v_pk_add_f32 v[52:53], v[232:233], v[52:53]
	s_nop 0
	v_pk_add_f32 v[52:53], v[76:77], v[52:53]
	s_nop 0
	v_pk_add_f32 v[52:53], v[120:121], v[52:53]
	s_nop 0
	v_pk_add_f32 v[52:53], v[78:79], v[52:53]
	s_nop 0
	v_add_f32_e32 v52, v52, v53
	v_add_f32_e32 v147, v147, v52

.Lml_c1o_done:
	s_mov_b32 s99, 1
	s_mov_b32 s100, 1
	s_branch .Lml_936x

.Lml_exit:
	s_cmp_eq_u32 s99, 0
	s_cbranch_scc1 .LBB0_938
	s_cmp_eq_u32 s100, 0
	s_cbranch_scc1 .Lml_fin_e
	v_exp_f32_e32 v247, v64
	v_exp_f32_e32 v246, v48
	v_exp_f32_e32 v215, v65
	v_exp_f32_e32 v214, v49
	v_exp_f32_e32 v217, v66
	v_exp_f32_e32 v216, v50
	v_exp_f32_e32 v219, v67
	v_exp_f32_e32 v223, v68
	v_exp_f32_e32 v69, v69
	v_exp_f32_e32 v225, v70
	v_exp_f32_e32 v71, v71
	v_pk_add_f32 v[48:49], v[246:247], 0 op_sel_hi:[1,0]
	v_exp_f32_e32 v218, v51
	v_pk_add_f32 v[48:49], v[214:215], v[48:49]
	v_cvt_pk_bf16_f32 v50, v223, v69
	v_pk_add_f32 v[220:221], v[216:217], v[48:49]
	v_cvt_pk_bf16_f32 v48, v247, v215
	v_cvt_pk_bf16_f32 v49, v217, v219
	v_cvt_pk_bf16_f32 v51, v225, v71
	v_exp_f32_e32 v227, v72
	v_exp_f32_e32 v73, v73
	s_waitcnt lgkmcnt(6)
	v_mfma_f32_32x32x16_bf16 v[0:15], v[120:123], v[48:51], v[0:15]
	v_exp_f32_e32 v229, v74
	v_exp_f32_e32 v75, v75
	v_exp_f32_e32 v231, v76
	v_exp_f32_e32 v77, v77
	v_exp_f32_e32 v121, v78
	v_exp_f32_e32 v79, v79
	v_cvt_pk_bf16_f32 v64, v227, v73
	s_waitcnt lgkmcnt(4)
	v_mfma_f32_32x32x16_bf16 v[16:31], v[112:115], v[48:51], v[16:31]
	v_cvt_pk_bf16_f32 v65, v229, v75
	v_cvt_pk_bf16_f32 v66, v231, v77
	v_cvt_pk_bf16_f32 v67, v121, v79
	v_exp_f32_e32 v222, v52
	v_exp_f32_e32 v68, v53
	v_exp_f32_e32 v224, v54
	v_exp_f32_e32 v70, v55
	s_waitcnt lgkmcnt(2)
	v_mfma_f32_32x32x16_bf16 v[0:15], v[124:127], v[64:67], v[0:15]
	ds_read_b64_tr_b16 v[48:49], v249 offset:24576
	ds_read_b64_tr_b16 v[50:51], v249 offset:26112
	v_exp_f32_e32 v226, v56
	v_exp_f32_e32 v72, v57
	v_exp_f32_e32 v228, v58
	v_exp_f32_e32 v74, v59
	ds_read_b64_tr_b16 v[52:53], v249 offset:27648
	ds_read_b64_tr_b16 v[54:55], v249 offset:29184
	ds_read_b64_tr_b16 v[58:59], v249 offset:26176
	ds_read_b64_tr_b16 v[56:57], v249 offset:24640
	v_exp_f32_e32 v230, v60
	s_waitcnt lgkmcnt(6)
	v_mfma_f32_32x32x16_bf16 v[16:31], v[116:119], v[64:67], v[16:31]
	v_cvt_pk_bf16_f32 v64, v246, v214
	v_cvt_pk_bf16_f32 v65, v216, v218
	v_cvt_pk_bf16_f32 v66, v222, v68
	v_cvt_pk_bf16_f32 v67, v224, v70
	v_exp_f32_e32 v76, v61
	v_exp_f32_e32 v120, v62
	v_exp_f32_e32 v78, v63
	s_waitcnt lgkmcnt(4)
	v_mfma_f32_32x32x16_bf16 v[0:15], v[48:51], v[64:67], v[0:15]
	v_add_f32_e64 v122, v218, v220
	v_add_f32_e64 v123, v219, v221
	v_cvt_pk_bf16_f32 v60, v226, v72
	v_cvt_pk_bf16_f32 v61, v228, v74
	v_cvt_pk_bf16_f32 v62, v230, v76
	v_cvt_pk_bf16_f32 v63, v120, v78
	ds_read_b64_tr_b16 v[50:51], v249 offset:29248
	ds_read_b64_tr_b16 v[48:49], v249 offset:27712
	s_waitcnt lgkmcnt(2)
	v_mfma_f32_32x32x16_bf16 v[16:31], v[56:59], v[64:67], v[16:31]
	v_mfma_f32_32x32x16_bf16 v[0:15], v[52:55], v[60:63], v[0:15]
	v_add_f32_e64 v52, v222, v122
	v_add_f32_e64 v53, v223, v123
	v_add_f32_e64 v52, v68, v52
	v_add_f32_e64 v53, v69, v53
	v_add_f32_e64 v52, v224, v52
	v_add_f32_e64 v53, v225, v53
	v_pk_add_f32 v[52:53], v[70:71], v[52:53]
	s_waitcnt lgkmcnt(0)
	v_mfma_f32_32x32x16_bf16 v[16:31], v[48:51], v[60:63], v[16:31]
	v_add_f32_e64 v52, v226, v52
	v_add_f32_e64 v53, v227, v53
	v_add_f32_e64 v52, v72, v52
	v_add_f32_e64 v53, v73, v53
	v_add_f32_e64 v52, v228, v52
	v_add_f32_e64 v53, v229, v53
	v_pk_add_f32 v[52:53], v[74:75], v[52:53]
	s_nop 0
	v_pk_add_f32 v[52:53], v[230:231], v[52:53]
	s_nop 0
	v_pk_add_f32 v[52:53], v[76:77], v[52:53]
	s_nop 0
	v_pk_add_f32 v[52:53], v[120:121], v[52:53]
	s_nop 0
	v_pk_add_f32 v[52:53], v[78:79], v[52:53]
	s_nop 0
	v_add_f32_e32 v52, v52, v53
	v_add_f32_e32 v147, v147, v52
	s_branch .LBB0_938
.Lml_fin_e:
	v_exp_f32_e32 v215, v64
	v_exp_f32_e32 v214, v48
	v_exp_f32_e32 v217, v65
	v_exp_f32_e32 v216, v49
	v_exp_f32_e32 v219, v66
	v_exp_f32_e32 v218, v50
	v_exp_f32_e32 v221, v67
	v_exp_f32_e32 v225, v68
	v_exp_f32_e32 v69, v69
	v_exp_f32_e32 v227, v70
	v_exp_f32_e32 v71, v71
	v_pk_add_f32 v[48:49], v[214:215], 0 op_sel_hi:[1,0]
	v_exp_f32_e32 v220, v51
	v_pk_add_f32 v[48:49], v[216:217], v[48:49]
	v_cvt_pk_bf16_f32 v50, v225, v69
	v_pk_add_f32 v[222:223], v[218:219], v[48:49]
	v_cvt_pk_bf16_f32 v48, v215, v217
	v_cvt_pk_bf16_f32 v49, v219, v221
	v_cvt_pk_bf16_f32 v51, v227, v71
	v_exp_f32_e32 v229, v72
	v_exp_f32_e32 v73, v73
	s_waitcnt lgkmcnt(6)
	v_mfma_f32_32x32x16_bf16 v[0:15], v[120:123], v[48:51], v[0:15]
	v_exp_f32_e32 v231, v74
	v_exp_f32_e32 v75, v75
	v_exp_f32_e32 v233, v76
	v_exp_f32_e32 v77, v77
	v_exp_f32_e32 v121, v78
	v_exp_f32_e32 v79, v79
	v_cvt_pk_bf16_f32 v64, v229, v73
	s_waitcnt lgkmcnt(4)
	v_mfma_f32_32x32x16_bf16 v[16:31], v[112:115], v[48:51], v[16:31]
	v_cvt_pk_bf16_f32 v65, v231, v75
	v_cvt_pk_bf16_f32 v66, v233, v77
	v_cvt_pk_bf16_f32 v67, v121, v79
	v_exp_f32_e32 v224, v52
	v_exp_f32_e32 v68, v53
	v_exp_f32_e32 v226, v54
	v_exp_f32_e32 v70, v55
	s_waitcnt lgkmcnt(2)
	v_mfma_f32_32x32x16_bf16 v[0:15], v[124:127], v[64:67], v[0:15]
	ds_read_b64_tr_b16 v[48:49], v248 offset:24576
	ds_read_b64_tr_b16 v[50:51], v248 offset:26112
	v_exp_f32_e32 v228, v56
	v_exp_f32_e32 v72, v57
	v_exp_f32_e32 v230, v58
	v_exp_f32_e32 v74, v59
	ds_read_b64_tr_b16 v[52:53], v248 offset:27648
	ds_read_b64_tr_b16 v[54:55], v248 offset:29184
	ds_read_b64_tr_b16 v[58:59], v248 offset:26176
	ds_read_b64_tr_b16 v[56:57], v248 offset:24640
	v_exp_f32_e32 v232, v60
	s_waitcnt lgkmcnt(6)
	v_mfma_f32_32x32x16_bf16 v[16:31], v[116:119], v[64:67], v[16:31]
	v_cvt_pk_bf16_f32 v64, v214, v216
	v_cvt_pk_bf16_f32 v65, v218, v220
	v_cvt_pk_bf16_f32 v66, v224, v68
	v_cvt_pk_bf16_f32 v67, v226, v70
	v_exp_f32_e32 v76, v61
	v_exp_f32_e32 v120, v62
	v_exp_f32_e32 v78, v63
	s_waitcnt lgkmcnt(4)
	v_mfma_f32_32x32x16_bf16 v[0:15], v[48:51], v[64:67], v[0:15]
	v_add_f32_e64 v122, v220, v222
	v_add_f32_e64 v123, v221, v223
	v_cvt_pk_bf16_f32 v60, v228, v72
	v_cvt_pk_bf16_f32 v61, v230, v74
	v_cvt_pk_bf16_f32 v62, v232, v76
	v_cvt_pk_bf16_f32 v63, v120, v78
	ds_read_b64_tr_b16 v[50:51], v248 offset:29248
	ds_read_b64_tr_b16 v[48:49], v248 offset:27712
	s_waitcnt lgkmcnt(2)
	v_mfma_f32_32x32x16_bf16 v[16:31], v[56:59], v[64:67], v[16:31]
	v_mfma_f32_32x32x16_bf16 v[0:15], v[52:55], v[60:63], v[0:15]
	v_add_f32_e64 v52, v224, v122
	v_add_f32_e64 v53, v225, v123
	v_add_f32_e64 v52, v68, v52
	v_add_f32_e64 v53, v69, v53
	v_add_f32_e64 v52, v226, v52
	v_add_f32_e64 v53, v227, v53
	v_pk_add_f32 v[52:53], v[70:71], v[52:53]
	s_waitcnt lgkmcnt(0)
	v_mfma_f32_32x32x16_bf16 v[16:31], v[48:51], v[60:63], v[16:31]
	v_add_f32_e64 v52, v228, v52
	v_add_f32_e64 v53, v229, v53
	v_add_f32_e64 v52, v72, v52
	v_add_f32_e64 v53, v73, v53
	v_add_f32_e64 v52, v230, v52
	v_add_f32_e64 v53, v231, v53
	v_pk_add_f32 v[52:53], v[74:75], v[52:53]
	s_nop 0
	v_pk_add_f32 v[52:53], v[232:233], v[52:53]
	s_nop 0
	v_pk_add_f32 v[52:53], v[76:77], v[52:53]
	s_nop 0
	v_pk_add_f32 v[52:53], v[120:121], v[52:53]
	s_nop 0
	v_pk_add_f32 v[52:53], v[78:79], v[52:53]
	s_nop 0
	v_add_f32_e32 v52, v52, v53
	v_add_f32_e32 v147, v147, v52
	s_branch .LBB0_938

	.amdhsa_kernel _Z10fwd_kernel4Args
		.amdhsa_group_segment_fixed_size 12288
		.amdhsa_private_segment_fixed_size 0
		.amdhsa_kernarg_size 528
		.amdhsa_user_sgpr_count 2
		.amdhsa_user_sgpr_dispatch_ptr 0
		.amdhsa_user_sgpr_queue_ptr 0
		.amdhsa_user_sgpr_kernarg_segment_ptr 1
		.amdhsa_user_sgpr_dispatch_id 0
		.amdhsa_user_sgpr_kernarg_preload_length 0
		.amdhsa_user_sgpr_kernarg_preload_offset 0
		.amdhsa_user_sgpr_private_segment_size 0
		.amdhsa_uses_dynamic_stack 0
		.amdhsa_enable_private_segment 0
		.amdhsa_system_sgpr_workgroup_id_x 1
		.amdhsa_system_sgpr_workgroup_id_y 0
		.amdhsa_system_sgpr_workgroup_id_z 0
		.amdhsa_system_sgpr_workgroup_info 0
		.amdhsa_system_vgpr_workitem_id 2
		.amdhsa_next_free_vgpr 256
		.amdhsa_next_free_sgpr 102
		.amdhsa_accum_offset 256
		.amdhsa_reserve_vcc 1
		.amdhsa_float_round_mode_32 0
		.amdhsa_float_round_mode_16_64 0
		.amdhsa_float_denorm_mode_32 3
		.amdhsa_float_denorm_mode_16_64 3
		.amdhsa_dx10_clamp 1
		.amdhsa_ieee_mode 1
		.amdhsa_fp16_overflow 0
		.amdhsa_tg_split 0
		.amdhsa_exception_fp_ieee_invalid_op 0
		.amdhsa_exception_fp_denorm_src 0
		.amdhsa_exception_fp_ieee_div_zero 0
		.amdhsa_exception_fp_ieee_overflow 0
		.amdhsa_exception_fp_ieee_underflow 0
		.amdhsa_exception_fp_ieee_inexact 0
		.amdhsa_exception_int_div_zero 0
	.end_amdhsa_kernel

amdhsa.kernels:
  - .agpr_count:     0
    .args:
      - .offset:         0
        .size:           272
        .value_kind:     by_value
      - .offset:         272
        .size:           4
        .value_kind:     hidden_block_count_x
      - .offset:         276
        .size:           4
        .value_kind:     hidden_block_count_y
      - .offset:         280
        .size:           4
        .value_kind:     hidden_block_count_z
      - .offset:         284
        .size:           2
        .value_kind:     hidden_group_size_x
      - .offset:         286
        .size:           2
        .value_kind:     hidden_group_size_y
      - .offset:         288
        .size:           2
        .value_kind:     hidden_group_size_z
      - .offset:         290
        .size:           2
        .value_kind:     hidden_remainder_x
      - .offset:         292
        .size:           2
        .value_kind:     hidden_remainder_y
      - .offset:         294
        .size:           2
        .value_kind:     hidden_remainder_z
      - .offset:         312
        .size:           8
        .value_kind:     hidden_global_offset_x
      - .offset:         320
        .size:           8
        .value_kind:     hidden_global_offset_y
      - .offset:         328
        .size:           8
        .value_kind:     hidden_global_offset_z
      - .offset:         336
        .size:           2
        .value_kind:     hidden_grid_dims
      - .offset:         360
        .size:           8
        .value_kind:     hidden_multigrid_sync_arg
      - .offset:         392
        .size:           4
        .value_kind:     hidden_dynamic_lds_size
    .group_segment_fixed_size: 12288
    .kernarg_segment_align: 8
    .kernarg_segment_size: 528
    .language:       OpenCL C
    .language_version:
      - 2
      - 0
    .max_flat_workgroup_size: 512
    .name:           _Z10fwd_kernel4Args
    .private_segment_fixed_size: 0
    .sgpr_count:     108
    .sgpr_spill_count: 67
    .symbol:         _Z10fwd_kernel4Args.kd
    .uniform_work_group_size: 1
    .uses_dynamic_stack: false
    .vgpr_count:     256
    .vgpr_spill_count: 0
    .wavefront_size: 64
